# speedup vs baseline: 1.0094x; 1.0042x over previous
; __device__ __forceinline__ void df_unit_p128(ATT_LAS unsigned char* lds, const bf16_t* Q, const bf16_t* __restrict__ K, const bf16_t* __restrict__ V, bf16_t* O, int b, int h, int qb,
;                                              float lam, float post, const float* __restrict__ sub_g, const int wv) {
;     ...
;     f32x16 S[4]; u32x4 wa[8], wb[8];
;     D8_QKP(0, qb == 0)
; #pragma unroll
;     for (int k_ = 0; k_ < 8; ++k_) { wa[k_] = (u32x4){0u, 0u, 0u, 0u}; wb[k_] = (u32x4){0u, 0u, 0u, 0u}; }
;     { float s0_ = 0.f, s1_ = 0.f;
; #pragma unroll
;       for (int j_ = 0; j_ < 16; ++j_) D8_SOFTC(j_, wa);
;       l += s0_ + s1_; }
.LBB0_218:
	v_and_b32_e32 v4, 15, v4
	s_lshl_b32 s39, s29, 3
	v_bitop3_b32 v6, s39, v4, v3 bitop3:0x36
	v_lshlrev_b32_e32 v4, 4, v4
	v_lshlrev_b32_e32 v82, 4, v6
	v_and_b32_e32 v4, 0xc0, v4
	v_lshlrev_b32_e32 v83, 8, v2
	v_lshlrev_b32_e32 v5, 5, v5
	v_lshl_or_b32 v3, v3, 8, v4
	v_or_b32_e32 v2, v82, v83
	v_and_or_b32 v3, v5, 32, v3
	s_mov_b32 s39, 0x10000
	v_add_u32_e32 v248, 0, v2
	v_or3_b32 v246, v3, v69, s39
	ds_read_b128 v[2:5], v248
	ds_read_b128 v[6:9], v248 offset:8192
	ds_read_b128 v[34:37], v248 offset:16384
	s_mov_b32 s39, 0
	s_waitcnt lgkmcnt(0)
	v_mfma_f32_32x32x16_bf16 v[18:33], v[2:5], v[154:157], 0
	ds_read_b128 v[50:53], v248 offset:24576
	v_mfma_f32_32x32x16_bf16 v[2:17], v[6:9], v[154:157], 0
	v_bitop3_b32 v38, v82, 32, v83 bitop3:0x36
	v_add_u32_e32 v249, 0, v38
	ds_read_b128 v[70:73], v249
	v_mfma_f32_32x32x16_bf16 v[34:49], v[34:37], v[154:157], 0
	ds_read_b128 v[74:77], v249 offset:8192
	s_waitcnt lgkmcnt(0)
	v_mfma_f32_32x32x16_bf16 v[50:65], v[50:53], v[154:157], 0
	ds_read_b128 v[78:81], v249 offset:16384
	v_mfma_f32_32x32x16_bf16 v[18:33], v[70:73], v[150:153], v[18:33]
	ds_read_b128 v[70:73], v249 offset:24576
	v_mfma_f32_32x32x16_bf16 v[2:17], v[74:77], v[150:153], v[2:17]
	v_bitop3_b32 v74, v82, 64, v83 bitop3:0x36
	v_add_u32_e32 v250, 0, v74
	ds_read_b128 v[74:77], v250
	s_waitcnt lgkmcnt(0)
	v_mfma_f32_32x32x16_bf16 v[34:49], v[78:81], v[150:153], v[34:49]
	ds_read_b128 v[78:81], v250 offset:8192
	v_mfma_f32_32x32x16_bf16 v[50:65], v[70:73], v[150:153], v[50:65]
	ds_read_b128 v[70:73], v250 offset:16384
	v_mfma_f32_32x32x16_bf16 v[18:33], v[74:77], v[146:149], v[18:33]
	ds_read_b128 v[74:77], v250 offset:24576
	s_waitcnt lgkmcnt(0)
	v_mfma_f32_32x32x16_bf16 v[2:17], v[78:81], v[146:149], v[2:17]
	s_movk_i32 s43, 0x60
	v_bitop3_b32 v78, v82, s43, v83 bitop3:0x36
	v_add_u32_e32 v251, 0, v78
	ds_read_b128 v[78:81], v251
	v_mfma_f32_32x32x16_bf16 v[34:49], v[70:73], v[146:149], v[34:49]
	ds_read_b128 v[70:73], v251 offset:8192
	v_mfma_f32_32x32x16_bf16 v[50:65], v[74:77], v[146:149], v[50:65]
	ds_read_b128 v[74:77], v251 offset:16384
	s_waitcnt lgkmcnt(0)
	v_mfma_f32_32x32x16_bf16 v[18:33], v[78:81], v[142:145], v[18:33]
	ds_read_b128 v[78:81], v251 offset:24576
	v_mfma_f32_32x32x16_bf16 v[2:17], v[70:73], v[142:145], v[2:17]
	v_mfma_f32_32x32x16_bf16 v[34:49], v[74:77], v[142:145], v[34:49]
	s_waitcnt lgkmcnt(0)
	v_mfma_f32_32x32x16_bf16 v[50:65], v[78:81], v[142:145], v[50:65]
	s_nop 6
	v_exp_f32_e32 v18, v18
	v_exp_f32_e32 v19, v19
	v_exp_f32_e32 v20, v20
	v_exp_f32_e32 v21, v21
	v_exp_f32_e32 v2, v2
	v_add_f32_e32 v70, v18, v19
	v_cvt_pk_bf16_f32 v158, v18, v19
	v_exp_f32_e32 v18, v22
	v_exp_f32_e32 v19, v23
	v_add_f32_e32 v71, v21, v20
	v_exp_f32_e32 v22, v24
	v_exp_f32_e32 v23, v25
	v_cvt_pk_bf16_f32 v159, v20, v21
	v_add_f32_e32 v20, v18, v19
	v_cvt_pk_bf16_f32 v160, v18, v19
	v_exp_f32_e32 v18, v26
	v_exp_f32_e32 v19, v27
	v_exp_f32_e32 v24, v28
	v_exp_f32_e32 v25, v29
	v_add_f32_e32 v70, 0, v70
	v_add_f32_e32 v71, 0, v71
	v_add_f32_e32 v21, v23, v22
	v_cvt_pk_bf16_f32 v161, v22, v23
	v_add_f32_e32 v22, v18, v19
	v_cvt_pk_bf16_f32 v162, v18, v19
	v_exp_f32_e32 v18, v30
	v_exp_f32_e32 v19, v31
	v_exp_f32_e32 v3, v3
	v_exp_f32_e32 v23, v33
	v_add_f32_e32 v20, v20, v70
	v_add_f32_e32 v21, v21, v71
	v_cvt_pk_bf16_f32 v163, v24, v25
	v_add_f32_e32 v20, v22, v20
	v_add_f32_e32 v22, v25, v24
	v_add_f32_e32 v21, v22, v21
	v_exp_f32_e32 v22, v32
	v_add_f32_e32 v24, v18, v19
	v_cvt_pk_bf16_f32 v164, v18, v19
	v_exp_f32_e32 v4, v4
	v_exp_f32_e32 v5, v5
	v_add_f32_e32 v18, v2, v3
	v_cvt_pk_bf16_f32 v166, v2, v3
	v_exp_f32_e32 v2, v6
	v_exp_f32_e32 v3, v7
	v_exp_f32_e32 v6, v8
	v_exp_f32_e32 v7, v9
	v_add_f32_e32 v19, v5, v4
	v_add_f32_e32 v20, v24, v20
	v_add_f32_e32 v24, v23, v22
	v_cvt_pk_bf16_f32 v167, v4, v5
	v_add_f32_e32 v4, v2, v3
	v_cvt_pk_bf16_f32 v168, v2, v3
	v_exp_f32_e32 v2, v10
	v_exp_f32_e32 v3, v11
	v_add_f32_e32 v21, v24, v21
	v_exp_f32_e32 v8, v12
	v_exp_f32_e32 v9, v13
	v_add_f32_e32 v5, v7, v6
	v_add_f32_e32 v18, v18, v20
	v_add_f32_e32 v19, v19, v21
	v_cvt_pk_bf16_f32 v169, v6, v7
	v_add_f32_e32 v4, v4, v18
	v_add_f32_e32 v5, v5, v19
	v_add_f32_e32 v6, v2, v3
	v_add_f32_e32 v4, v6, v4
	v_add_f32_e32 v6, v9, v8
	v_cvt_pk_bf16_f32 v170, v2, v3
	v_exp_f32_e32 v2, v14
	v_exp_f32_e32 v3, v15
	v_add_f32_e32 v5, v6, v5
	v_exp_f32_e32 v6, v16
	v_exp_f32_e32 v7, v17
	v_cndmask_b32_e64 v35, v35, v244, s[18:19]
	v_cndmask_b32_e64 v34, v34, v244, s[18:19]
	v_cvt_pk_bf16_f32 v171, v8, v9
	v_add_f32_e32 v8, v2, v3
	v_cndmask_b32_e64 v37, v37, v244, s[18:19]
	v_cndmask_b32_e64 v36, v36, v244, s[18:19]
	v_add_f32_e32 v4, v8, v4
	v_add_f32_e32 v8, v7, v6
	v_cvt_pk_bf16_f32 v172, v2, v3
	v_exp_f32_e32 v2, v34
	v_exp_f32_e32 v3, v35
	v_add_f32_e32 v5, v8, v5
	v_exp_f32_e32 v8, v36
	v_exp_f32_e32 v9, v37
	v_cndmask_b32_e64 v39, v39, v244, s[18:19]
	v_cndmask_b32_e64 v38, v38, v244, s[18:19]
	v_cvt_pk_bf16_f32 v173, v6, v7
	v_add_f32_e32 v6, v2, v3
	v_cndmask_b32_e64 v41, v41, v244, s[18:19]
	v_cndmask_b32_e64 v40, v40, v244, s[18:19]
	v_add_f32_e32 v4, v6, v4
	v_add_f32_e32 v6, v9, v8
	v_cvt_pk_bf16_f32 v174, v2, v3
	v_exp_f32_e32 v2, v38
	v_exp_f32_e32 v3, v39
	v_add_f32_e32 v5, v6, v5
	v_exp_f32_e32 v6, v40
	v_exp_f32_e32 v7, v41
	v_cndmask_b32_e64 v43, v43, v244, s[18:19]
	v_cndmask_b32_e64 v42, v42, v244, s[18:19]
	v_cvt_pk_bf16_f32 v175, v8, v9
	v_add_f32_e32 v8, v2, v3
	v_cndmask_b32_e64 v45, v45, v244, s[18:19]
	v_cndmask_b32_e64 v44, v44, v244, s[18:19]
	v_add_f32_e32 v4, v8, v4
	v_add_f32_e32 v8, v7, v6
	v_cvt_pk_bf16_f32 v176, v2, v3
	v_exp_f32_e32 v2, v42
	v_exp_f32_e32 v3, v43
	v_add_f32_e32 v5, v8, v5
; #define D8_FULL(WC_, WN_, t_, MASK_) do { const int tt = (t_); D8_HEAD(tt) D8_QKP(tt + 1, MASK_) D8_PVX(tt, WC_, true, WN_) } while (0)
; __device__ __forceinline__ void df_unit_p128(ATT_LAS unsigned char* lds, const bf16_t* Q, const bf16_t* __restrict__ K, const bf16_t* __restrict__ V, bf16_t* O, int b, int h, int qb,
;                                              float lam, float post, const float* __restrict__ sub_g, const int wv) {
;     ...
;     f32x16 S[4]; u32x4 wa[8], wb[8];
;     D8_QKP(0, qb == 0)
; #pragma unroll
;     for (int k_ = 0; k_ < 8; ++k_) { wa[k_] = (u32x4){0u, 0u, 0u, 0u}; wb[k_] = (u32x4){0u, 0u, 0u, 0u}; }
;     { float s0_ = 0.f, s1_ = 0.f;
; #pragma unroll
;       for (int j_ = 0; j_ < 16; ++j_) D8_SOFTC(j_, wa);
;       l += s0_ + s1_; }
;     int T = 0;
;     for (; T + 2 <= qb - 1; T += 2) { D8_FULL(wa, wb, T, false); D8_FULL(wb, wa, T + 1, false); }
	v_exp_f32_e32 v8, v44
	v_exp_f32_e32 v9, v45
	v_cndmask_b32_e64 v47, v47, v244, s[18:19]
	v_cndmask_b32_e64 v46, v46, v244, s[18:19]
	v_cvt_pk_bf16_f32 v177, v6, v7
	v_add_f32_e32 v6, v2, v3
	v_cndmask_b32_e64 v49, v49, v244, s[18:19]
	v_cndmask_b32_e64 v48, v48, v244, s[18:19]
	v_add_f32_e32 v4, v6, v4
	v_add_f32_e32 v6, v9, v8
	v_cvt_pk_bf16_f32 v178, v2, v3
	v_exp_f32_e32 v2, v46
	v_exp_f32_e32 v3, v47
	v_add_f32_e32 v5, v6, v5
	v_exp_f32_e32 v6, v48
	v_exp_f32_e32 v7, v49
	v_cndmask_b32_e64 v51, v51, v244, s[18:19]
	v_cndmask_b32_e64 v50, v50, v244, s[18:19]
	v_cvt_pk_bf16_f32 v179, v8, v9
	v_add_f32_e32 v8, v2, v3
	v_cndmask_b32_e64 v53, v53, v244, s[18:19]
	v_cndmask_b32_e64 v52, v52, v244, s[18:19]
	v_add_f32_e32 v4, v8, v4
	v_add_f32_e32 v8, v7, v6
	v_cvt_pk_bf16_f32 v180, v2, v3
	v_exp_f32_e32 v2, v50
	v_exp_f32_e32 v3, v51
	v_add_f32_e32 v5, v8, v5
	v_exp_f32_e32 v8, v52
	v_exp_f32_e32 v9, v53
	v_cndmask_b32_e64 v55, v55, v244, s[18:19]
	v_cndmask_b32_e64 v54, v54, v244, s[18:19]
	v_cvt_pk_bf16_f32 v181, v6, v7
	v_add_f32_e32 v6, v2, v3
	v_cndmask_b32_e64 v57, v57, v244, s[18:19]
	v_cndmask_b32_e64 v56, v56, v244, s[18:19]
	v_add_f32_e32 v4, v6, v4
	v_add_f32_e32 v6, v9, v8
	v_cvt_pk_bf16_f32 v182, v2, v3
	v_exp_f32_e32 v2, v54
	v_exp_f32_e32 v3, v55
	v_add_f32_e32 v5, v6, v5
	v_exp_f32_e32 v6, v56
	v_exp_f32_e32 v7, v57
	v_cndmask_b32_e64 v59, v59, v244, s[18:19]
	v_cndmask_b32_e64 v58, v58, v244, s[18:19]
	v_cvt_pk_bf16_f32 v183, v8, v9
	v_add_f32_e32 v8, v2, v3
	v_cndmask_b32_e64 v61, v61, v244, s[18:19]
	v_cndmask_b32_e64 v60, v60, v244, s[18:19]
	v_add_f32_e32 v4, v8, v4
	v_add_f32_e32 v8, v7, v6
	v_cvt_pk_bf16_f32 v184, v2, v3
	v_exp_f32_e32 v2, v58
	v_exp_f32_e32 v3, v59
	v_add_f32_e32 v5, v8, v5
	v_exp_f32_e32 v8, v60
	v_exp_f32_e32 v9, v61
	v_cndmask_b32_e64 v63, v63, v244, s[18:19]
	v_cndmask_b32_e64 v62, v62, v244, s[18:19]
	v_cvt_pk_bf16_f32 v185, v6, v7
	v_add_f32_e32 v6, v2, v3
	v_cndmask_b32_e64 v65, v65, v244, s[18:19]
	v_cndmask_b32_e64 v64, v64, v244, s[18:19]
	v_add_f32_e32 v4, v6, v4
	v_add_f32_e32 v6, v9, v8
	v_cvt_pk_bf16_f32 v186, v2, v3
	v_exp_f32_e32 v2, v62
	v_exp_f32_e32 v3, v63
	v_add_f32_e32 v5, v6, v5
	v_exp_f32_e32 v6, v64
	v_exp_f32_e32 v7, v65
	v_cvt_pk_bf16_f32 v187, v8, v9
	v_add_f32_e32 v8, v2, v3
	v_add_f32_e32 v4, v8, v4
	v_add_f32_e32 v8, v7, v6
	v_add_f32_e32 v5, v8, v5
	v_cvt_pk_bf16_f32 v188, v2, v3
	v_add_f32_e32 v2, v5, v4
	v_cvt_pk_bf16_f32 v165, v22, v23
	v_cvt_pk_bf16_f32 v189, v6, v7
	v_add_f32_e32 v247, 0, v2
	s_cmp_lt_u32 s25, 3
	v_add_u32_e32 v252, 0, v246
	s_cbranch_scc1 .LBB0_222
	s_add_i32 s18, 0, 0x8000
	s_add_i32 s33, s33, s18
	v_add_u32_e32 v253, s18, v246
	s_and_b32 s18, s24, 7
	s_lshl_b32 s18, s18, 8
	s_add_i32 s19, s7, 0x8000
	s_or_b32 s16, s16, s18
	v_readlane_b32 s44, v254, 1
	v_add3_u32 v2, v68, s40, v69
	v_readlane_b32 s45, v254, 2
	s_add_u32 s16, s44, s16
	v_lshl_add_u32 v228, v2, 1, s42
	v_mov_b32_e32 v2, 0
	v_mov_b64_e32 v[216:217], 0x1ff
	v_mov_b64_e32 v[214:215], 0x200
	v_mov_b64_e32 v[212:213], 0x5ff
	v_mov_b64_e32 v[210:211], 0x600
	v_add3_u32 v226, s41, v66, v67
	v_mov_b32_e32 v227, v1
	s_addc_u32 s17, s45, s17
	v_mov_b32_e32 v229, v1
	v_mov_b32_e32 v3, v2
	v_mov_b32_e32 v4, v2
	v_mov_b32_e32 v5, v2
	v_mov_b32_e32 v6, v2
	v_mov_b32_e32 v7, v2
	v_mov_b32_e32 v8, v2
	v_mov_b32_e32 v9, v2
	v_mov_b32_e32 v10, v2
	v_mov_b32_e32 v11, v2
	v_mov_b32_e32 v12, v2
	v_mov_b32_e32 v13, v2
	v_mov_b32_e32 v14, v2
	v_mov_b32_e32 v15, v2
	v_mov_b32_e32 v16, v2
	v_mov_b32_e32 v17, v2
	v_mov_b32_e32 v50, v2
	v_mov_b32_e32 v51, v2
	v_mov_b32_e32 v52, v2
	v_mov_b32_e32 v53, v2
	v_mov_b32_e32 v54, v2
	v_mov_b32_e32 v55, v2
	v_mov_b32_e32 v56, v2
	v_mov_b32_e32 v57, v2
	v_mov_b32_e32 v58, v2
	v_mov_b32_e32 v59, v2
	v_mov_b32_e32 v60, v2
	v_mov_b32_e32 v61, v2
	v_mov_b32_e32 v62, v2
	v_mov_b32_e32 v63, v2
	v_mov_b32_e32 v64, v2
	v_mov_b32_e32 v65, v2
	v_mov_b32_e32 v34, v2
	v_mov_b32_e32 v35, v2
	v_mov_b32_e32 v36, v2
	v_mov_b32_e32 v37, v2
	v_mov_b32_e32 v38, v2
	v_mov_b32_e32 v39, v2
	v_mov_b32_e32 v40, v2
	v_mov_b32_e32 v41, v2
	v_mov_b32_e32 v42, v2
	v_mov_b32_e32 v43, v2
	v_mov_b32_e32 v44, v2
	v_mov_b32_e32 v45, v2
	v_mov_b32_e32 v46, v2
	v_mov_b32_e32 v47, v2
	v_mov_b32_e32 v48, v2
	v_mov_b32_e32 v49, v2
	v_mov_b32_e32 v18, v2
	v_mov_b32_e32 v19, v2
	v_mov_b32_e32 v20, v2
	v_mov_b32_e32 v21, v2
	v_mov_b32_e32 v22, v2
	v_mov_b32_e32 v23, v2
	v_mov_b32_e32 v24, v2
	v_mov_b32_e32 v25, v2
	v_mov_b32_e32 v26, v2
	v_mov_b32_e32 v27, v2
	v_mov_b32_e32 v28, v2
	v_mov_b32_e32 v29, v2
	v_mov_b32_e32 v30, v2
	v_mov_b32_e32 v31, v2
	v_mov_b32_e32 v32, v2
	v_mov_b32_e32 v33, v2
	s_mov_b64 s[42:43], 0xe480000
	s_mov_b64 s[44:45], 0xe4c0000
	s_nop 0
; __device__ __forceinline__ void df_unit_p128(ATT_LAS unsigned char* lds, const bf16_t* Q, const bf16_t* __restrict__ K, const bf16_t* __restrict__ V, bf16_t* O, int b, int h, int qb,
;                                              float lam, float post, const float* __restrict__ sub_g, const int wv) {
;     ...
;     const int kxb = r32 * 256 + (((mp * 8 + hi) ^ (r32 & 15)) * 16);
;     const int vread = D8_V0 + ((lane >> 4) & 1) * 32 + (lane & 3) * 8 + (4 * hi + ((lane & 15) >> 2)) * 64;
.LBB0_220:
	v_lshl_add_u64 v[238:239], s[16:17], 0, v[226:227]
	s_mov_b32 m0, s35
	s_waitcnt vmcnt(0) lgkmcnt(0)
	s_barrier
	ds_read_b128 v[66:69], v248 offset:32768
	ds_read_b128 v[70:73], v249 offset:32768
	ds_read_b128 v[74:77], v250 offset:32768
	ds_read_b128 v[78:81], v251 offset:32768
	v_lshl_add_u64 v[216:217], v[238:239], 0, s[42:43]
	v_lshl_add_u64 v[232:233], s[16:17], 0, v[224:225]
	global_load_lds_dwordx4 v[216:217], off
	s_waitcnt lgkmcnt(3)
	v_mfma_f32_32x32x16_bf16 v[114:129], v[66:69], v[154:157], 0
	ds_read_b128 v[66:69], v248 offset:40960
	v_lshl_add_u64 v[216:217], v[232:233], 0, s[42:43]
	s_mov_b32 m0, s36
	v_lshl_add_u64 v[234:235], s[16:17], 0, v[222:223]
	global_load_lds_dwordx4 v[216:217], off
	s_waitcnt lgkmcnt(3)
	v_mfma_f32_32x32x16_bf16 v[114:129], v[70:73], v[150:153], v[114:129]
	ds_read_b128 v[70:73], v249 offset:40960
	v_lshl_add_u64 v[216:217], v[234:235], 0, s[42:43]
	s_mov_b32 m0, s37
	v_lshl_add_u64 v[236:237], s[16:17], 0, v[220:221]
	global_load_lds_dwordx4 v[216:217], off
	s_waitcnt lgkmcnt(3)
	v_mfma_f32_32x32x16_bf16 v[114:129], v[74:77], v[146:149], v[114:129]
	ds_read_b128 v[74:77], v250 offset:40960
	v_lshl_add_u64 v[216:217], v[236:237], 0, s[42:43]
	s_mov_b32 m0, s38
	v_lshl_add_u64 v[230:231], s[16:17], 0, v[228:229]
	s_mov_b64 s[40:41], 0x12440000
	global_load_lds_dwordx4 v[216:217], off
	s_waitcnt lgkmcnt(3)
	v_mfma_f32_32x32x16_bf16 v[114:129], v[78:81], v[142:145], v[114:129]
	ds_read_b128 v[78:81], v251 offset:40960
	v_lshl_add_u64 v[216:217], v[230:231], 0, s[40:41]
	s_mov_b32 m0, s19
	s_mov_b64 s[40:41], 0x12448000
	global_load_lds_dwordx4 v[216:217], off
	s_waitcnt lgkmcnt(3)
	v_mfma_f32_32x32x16_bf16 v[98:113], v[66:69], v[154:157], 0
	ds_read_b128 v[66:69], v248 offset:49152
	v_lshl_add_u64 v[216:217], v[230:231], 0, s[40:41]
	s_add_i32 m0, s7, 0x8400
	s_mov_b64 s[40:41], 0x12450000
	global_load_lds_dwordx4 v[216:217], off
	s_waitcnt lgkmcnt(3)
	v_mfma_f32_32x32x16_bf16 v[98:113], v[70:73], v[150:153], v[98:113]
	ds_read_b128 v[70:73], v249 offset:49152
	v_lshl_add_u64 v[216:217], v[230:231], 0, s[40:41]
	s_add_i32 m0, s7, 0x8800
	s_mov_b64 s[40:41], 0x12458000
	global_load_lds_dwordx4 v[216:217], off
	s_waitcnt lgkmcnt(3)
	v_mfma_f32_32x32x16_bf16 v[98:113], v[74:77], v[146:149], v[98:113]
	ds_read_b128 v[74:77], v250 offset:49152
	v_lshl_add_u64 v[216:217], v[230:231], 0, s[40:41]
	s_add_i32 m0, s7, 0x8c00
	s_mov_b32 s18, s39
	global_load_lds_dwordx4 v[216:217], off
	s_waitcnt lgkmcnt(3)
	v_mfma_f32_32x32x16_bf16 v[98:113], v[78:81], v[142:145], v[98:113]
	v_exp_f32_e32 v114, v114
	v_exp_f32_e32 v115, v115
	v_exp_f32_e32 v116, v116
	v_exp_f32_e32 v117, v117
	ds_read_b128 v[78:81], v251 offset:49152
	s_waitcnt lgkmcnt(3)
	v_mfma_f32_32x32x16_bf16 v[82:97], v[66:69], v[154:157], 0
	v_add_f32_e32 v210, v114, v115
	v_add_f32_e32 v211, v117, v116
	v_cvt_pk_bf16_f32 v130, v114, v115
	v_cvt_pk_bf16_f32 v131, v116, v117
	ds_read_b128 v[194:197], v248 offset:57344
	s_waitcnt lgkmcnt(3)
	v_mfma_f32_32x32x16_bf16 v[82:97], v[70:73], v[150:153], v[82:97]
	v_exp_f32_e32 v118, v118
	v_exp_f32_e32 v119, v119
	v_exp_f32_e32 v120, v120
	v_exp_f32_e32 v121, v121
	ds_read_b128 v[198:201], v249 offset:57344
	s_waitcnt lgkmcnt(3)
	v_mfma_f32_32x32x16_bf16 v[82:97], v[74:77], v[146:149], v[82:97]
	v_add_f32_e32 v212, v118, v119
	v_add_f32_e32 v210, v212, v210
	v_add_f32_e32 v213, v121, v120
	v_add_f32_e32 v211, v213, v211
	v_cvt_pk_bf16_f32 v132, v118, v119
	v_cvt_pk_bf16_f32 v133, v120, v121
	ds_read_b128 v[202:205], v250 offset:57344
	s_waitcnt lgkmcnt(3)
	v_mfma_f32_32x32x16_bf16 v[82:97], v[78:81], v[142:145], v[82:97]
	v_exp_f32_e32 v122, v122
	v_exp_f32_e32 v123, v123
	v_exp_f32_e32 v124, v124
	v_exp_f32_e32 v125, v125
	ds_read_b128 v[206:209], v251 offset:57344
	s_waitcnt lgkmcnt(3)
	v_mfma_f32_32x32x16_bf16 v[66:81], v[194:197], v[154:157], 0
	v_add_f32_e32 v212, v122, v123
	v_add_f32_e32 v210, v212, v210
	v_add_f32_e32 v213, v125, v124
	v_add_f32_e32 v211, v213, v211
	v_cvt_pk_bf16_f32 v134, v122, v123
	v_cvt_pk_bf16_f32 v135, v124, v125
	s_waitcnt lgkmcnt(2)
	v_mfma_f32_32x32x16_bf16 v[66:81], v[198:201], v[150:153], v[66:81]
	v_exp_f32_e32 v126, v126
	v_exp_f32_e32 v127, v127
	v_exp_f32_e32 v128, v128
	v_exp_f32_e32 v129, v129
	ds_read_b64_tr_b16 v[214:215], v252
	ds_read_b64_tr_b16 v[216:217], v252 offset:512
	s_waitcnt lgkmcnt(3)
	v_mfma_f32_32x32x16_bf16 v[66:81], v[202:205], v[146:149], v[66:81]
	v_add_f32_e32 v212, v126, v127
	v_add_f32_e32 v210, v212, v210
	v_add_f32_e32 v213, v129, v128
	v_add_f32_e32 v211, v213, v211
	v_cvt_pk_bf16_f32 v136, v126, v127
	v_cvt_pk_bf16_f32 v137, v128, v129
	ds_read_b64_tr_b16 v[114:115], v252 offset:1024
	ds_read_b64_tr_b16 v[116:117], v252 offset:1536
	s_waitcnt lgkmcnt(4)
	v_mfma_f32_32x32x16_bf16 v[66:81], v[206:209], v[142:145], v[66:81]
	v_exp_f32_e32 v98, v98
	v_exp_f32_e32 v99, v99
	v_exp_f32_e32 v100, v100
	v_exp_f32_e32 v101, v101
	s_waitcnt lgkmcnt(2)
	v_mfma_f32_32x32x16_bf16 v[2:17], v[214:217], v[158:161], v[2:17]
	ds_read_b64_tr_b16 v[118:119], v252 offset:2048
	ds_read_b64_tr_b16 v[120:121], v252 offset:2560
	v_add_f32_e32 v212, v98, v99
	v_add_f32_e32 v210, v212, v210
	v_add_f32_e32 v213, v101, v100
	v_add_f32_e32 v211, v213, v211
	v_cvt_pk_bf16_f32 v138, v98, v99
	v_cvt_pk_bf16_f32 v139, v100, v101
	s_waitcnt lgkmcnt(2)
	v_mfma_f32_32x32x16_bf16 v[2:17], v[114:117], v[162:165], v[2:17]
	ds_read_b64_tr_b16 v[214:215], v252 offset:3072
	ds_read_b64_tr_b16 v[216:217], v252 offset:3584
	s_waitcnt lgkmcnt(2)
	v_mfma_f32_32x32x16_bf16 v[2:17], v[118:121], v[166:169], v[2:17]
	ds_read_b64_tr_b16 v[114:115], v252 offset:4096
	ds_read_b64_tr_b16 v[116:117], v252 offset:4608
	v_exp_f32_e32 v102, v102
	v_exp_f32_e32 v103, v103
	v_exp_f32_e32 v104, v104
	v_exp_f32_e32 v105, v105
	s_waitcnt lgkmcnt(2)
	v_mfma_f32_32x32x16_bf16 v[2:17], v[214:217], v[170:173], v[2:17]
	ds_read_b64_tr_b16 v[118:119], v252 offset:5120
	ds_read_b64_tr_b16 v[120:121], v252 offset:5632
	v_add_f32_e32 v212, v102, v103
	v_add_f32_e32 v210, v212, v210
	v_add_f32_e32 v213, v105, v104
	v_add_f32_e32 v211, v213, v211
	v_cvt_pk_bf16_f32 v140, v102, v103
	v_cvt_pk_bf16_f32 v141, v104, v105
	s_waitcnt lgkmcnt(2)
	v_mfma_f32_32x32x16_bf16 v[2:17], v[114:117], v[174:177], v[2:17]
	ds_read_b64_tr_b16 v[214:215], v252 offset:6144
	ds_read_b64_tr_b16 v[216:217], v252 offset:6656
	s_waitcnt lgkmcnt(2)
	v_mfma_f32_32x32x16_bf16 v[2:17], v[118:121], v[178:181], v[2:17]
	ds_read_b64_tr_b16 v[114:115], v252 offset:7168
	ds_read_b64_tr_b16 v[116:117], v252 offset:7680
	v_exp_f32_e32 v106, v106
	v_exp_f32_e32 v107, v107
	v_exp_f32_e32 v108, v108
	v_exp_f32_e32 v109, v109
	s_waitcnt lgkmcnt(2)
	v_mfma_f32_32x32x16_bf16 v[2:17], v[214:217], v[182:185], v[2:17]
	ds_read_b64_tr_b16 v[118:119], v252 offset:8192
	ds_read_b64_tr_b16 v[120:121], v252 offset:8704
	v_add_f32_e32 v212, v106, v107
	v_add_f32_e32 v210, v212, v210
	v_add_f32_e32 v213, v109, v108
	v_add_f32_e32 v211, v213, v211
	v_cvt_pk_bf16_f32 v190, v106, v107
	v_cvt_pk_bf16_f32 v191, v108, v109
	s_waitcnt lgkmcnt(2)
	v_mfma_f32_32x32x16_bf16 v[2:17], v[114:117], v[186:189], v[2:17]
	ds_read_b64_tr_b16 v[214:215], v252 offset:9216
	ds_read_b64_tr_b16 v[216:217], v252 offset:9728
	v_exp_f32_e32 v110, v110
	v_exp_f32_e32 v111, v111
	v_exp_f32_e32 v112, v112
	v_exp_f32_e32 v113, v113
	s_waitcnt lgkmcnt(2)
	v_mfma_f32_32x32x16_bf16 v[50:65], v[118:121], v[158:161], v[50:65]
	ds_read_b64_tr_b16 v[114:115], v252 offset:10240
	ds_read_b64_tr_b16 v[116:117], v252 offset:10752
	s_waitcnt lgkmcnt(2)
	v_mfma_f32_32x32x16_bf16 v[50:65], v[214:217], v[162:165], v[50:65]
	ds_read_b64_tr_b16 v[118:119], v252 offset:11264
	ds_read_b64_tr_b16 v[120:121], v252 offset:11776
	v_add_f32_e32 v212, v110, v111
	v_add_f32_e32 v210, v212, v210
	v_add_f32_e32 v213, v113, v112
	v_add_f32_e32 v211, v213, v211
	v_cvt_pk_bf16_f32 v192, v110, v111
	v_cvt_pk_bf16_f32 v193, v112, v113
	s_waitcnt lgkmcnt(2)
	v_mfma_f32_32x32x16_bf16 v[50:65], v[114:117], v[166:169], v[50:65]
	ds_read_b64_tr_b16 v[214:215], v252 offset:12288
	ds_read_b64_tr_b16 v[216:217], v252 offset:12800
	v_exp_f32_e32 v82, v82
	v_exp_f32_e32 v83, v83
	v_exp_f32_e32 v84, v84
	v_exp_f32_e32 v85, v85
	s_waitcnt lgkmcnt(2)
	v_mfma_f32_32x32x16_bf16 v[50:65], v[118:121], v[170:173], v[50:65]
	ds_read_b64_tr_b16 v[114:115], v252 offset:13312
	ds_read_b64_tr_b16 v[116:117], v252 offset:13824
	s_waitcnt lgkmcnt(2)
	v_mfma_f32_32x32x16_bf16 v[50:65], v[214:217], v[174:177], v[50:65]
	ds_read_b64_tr_b16 v[118:119], v252 offset:14336
	ds_read_b64_tr_b16 v[120:121], v252 offset:14848
	v_add_f32_e32 v212, v82, v83
	v_add_f32_e32 v210, v212, v210
	v_add_f32_e32 v213, v85, v84
	v_add_f32_e32 v211, v213, v211
	v_cvt_pk_bf16_f32 v194, v82, v83
	v_cvt_pk_bf16_f32 v195, v84, v85
	s_waitcnt lgkmcnt(2)
	v_mfma_f32_32x32x16_bf16 v[50:65], v[114:117], v[178:181], v[50:65]
	ds_read_b64_tr_b16 v[214:215], v252 offset:15360
	ds_read_b64_tr_b16 v[216:217], v252 offset:15872
	v_exp_f32_e32 v86, v86
	v_exp_f32_e32 v87, v87
	v_exp_f32_e32 v88, v88
	v_exp_f32_e32 v89, v89
	s_waitcnt lgkmcnt(2)
	v_mfma_f32_32x32x16_bf16 v[50:65], v[118:121], v[182:185], v[50:65]
	ds_read_b64_tr_b16 v[114:115], v252 offset:16384
	ds_read_b64_tr_b16 v[116:117], v252 offset:16896
	v_add_f32_e32 v212, v86, v87
	v_add_f32_e32 v210, v212, v210
	v_add_f32_e32 v213, v89, v88
	v_add_f32_e32 v211, v213, v211
	v_cvt_pk_bf16_f32 v196, v86, v87
	v_cvt_pk_bf16_f32 v197, v88, v89
	s_waitcnt lgkmcnt(2)
	v_mfma_f32_32x32x16_bf16 v[50:65], v[214:217], v[186:189], v[50:65]
	ds_read_b64_tr_b16 v[118:119], v252 offset:17408
	ds_read_b64_tr_b16 v[120:121], v252 offset:17920
	s_waitcnt lgkmcnt(2)
	v_mfma_f32_32x32x16_bf16 v[34:49], v[114:117], v[158:161], v[34:49]
	ds_read_b64_tr_b16 v[214:215], v252 offset:18432
	ds_read_b64_tr_b16 v[216:217], v252 offset:18944
	v_exp_f32_e32 v90, v90
	v_exp_f32_e32 v91, v91
	v_exp_f32_e32 v92, v92
	v_exp_f32_e32 v93, v93
	s_waitcnt lgkmcnt(2)
	v_mfma_f32_32x32x16_bf16 v[34:49], v[118:121], v[162:165], v[34:49]
	ds_read_b64_tr_b16 v[114:115], v252 offset:19456
	ds_read_b64_tr_b16 v[116:117], v252 offset:19968
	v_add_f32_e32 v212, v90, v91
	v_add_f32_e32 v210, v212, v210
	v_add_f32_e32 v213, v93, v92
	v_add_f32_e32 v211, v213, v211
	v_cvt_pk_bf16_f32 v198, v90, v91
	v_cvt_pk_bf16_f32 v199, v92, v93
	s_waitcnt lgkmcnt(2)
	v_mfma_f32_32x32x16_bf16 v[34:49], v[214:217], v[166:169], v[34:49]
	ds_read_b64_tr_b16 v[118:119], v252 offset:20480
	ds_read_b64_tr_b16 v[120:121], v252 offset:20992
	v_exp_f32_e32 v94, v94
	v_exp_f32_e32 v95, v95
	v_exp_f32_e32 v96, v96
	v_exp_f32_e32 v97, v97
	s_waitcnt lgkmcnt(2)
	v_mfma_f32_32x32x16_bf16 v[34:49], v[114:117], v[170:173], v[34:49]
	ds_read_b64_tr_b16 v[214:215], v252 offset:21504
	ds_read_b64_tr_b16 v[216:217], v252 offset:22016
	s_waitcnt lgkmcnt(2)
	v_mfma_f32_32x32x16_bf16 v[34:49], v[118:121], v[174:177], v[34:49]
	ds_read_b64_tr_b16 v[114:115], v252 offset:22528
	ds_read_b64_tr_b16 v[116:117], v252 offset:23040
	v_add_f32_e32 v212, v94, v95
	v_add_f32_e32 v210, v212, v210
	v_add_f32_e32 v213, v97, v96
	v_add_f32_e32 v211, v213, v211
	v_cvt_pk_bf16_f32 v200, v94, v95
	v_cvt_pk_bf16_f32 v201, v96, v97
	s_waitcnt lgkmcnt(2)
	v_mfma_f32_32x32x16_bf16 v[34:49], v[214:217], v[178:181], v[34:49]
	ds_read_b64_tr_b16 v[118:119], v252 offset:23552
	ds_read_b64_tr_b16 v[120:121], v252 offset:24064
	v_exp_f32_e32 v66, v66
	v_exp_f32_e32 v67, v67
	v_exp_f32_e32 v68, v68
	v_exp_f32_e32 v69, v69
	s_waitcnt lgkmcnt(2)
	v_mfma_f32_32x32x16_bf16 v[34:49], v[114:117], v[182:185], v[34:49]
	ds_read_b64_tr_b16 v[214:215], v252 offset:24576
	ds_read_b64_tr_b16 v[216:217], v252 offset:25088
	s_waitcnt lgkmcnt(2)
	v_mfma_f32_32x32x16_bf16 v[34:49], v[118:121], v[186:189], v[34:49]
	ds_read_b64_tr_b16 v[114:115], v252 offset:25600
	ds_read_b64_tr_b16 v[116:117], v252 offset:26112
	v_add_f32_e32 v212, v66, v67
	v_add_f32_e32 v210, v212, v210
	v_add_f32_e32 v213, v69, v68
	v_add_f32_e32 v211, v213, v211
	v_cvt_pk_bf16_f32 v202, v66, v67
	v_cvt_pk_bf16_f32 v203, v68, v69
	s_waitcnt lgkmcnt(2)
	v_mfma_f32_32x32x16_bf16 v[18:33], v[214:217], v[158:161], v[18:33]
	ds_read_b64_tr_b16 v[118:119], v252 offset:26624
	ds_read_b64_tr_b16 v[120:121], v252 offset:27136
	v_exp_f32_e32 v70, v70
	v_exp_f32_e32 v71, v71
	v_exp_f32_e32 v72, v72
	v_exp_f32_e32 v73, v73
	s_waitcnt lgkmcnt(2)
	v_mfma_f32_32x32x16_bf16 v[18:33], v[114:117], v[162:165], v[18:33]
	ds_read_b64_tr_b16 v[214:215], v252 offset:27648
	ds_read_b64_tr_b16 v[216:217], v252 offset:28160
	v_add_f32_e32 v212, v70, v71
	v_add_f32_e32 v210, v212, v210
	v_add_f32_e32 v213, v73, v72
	v_add_f32_e32 v211, v213, v211
	v_cvt_pk_bf16_f32 v204, v70, v71
	v_cvt_pk_bf16_f32 v205, v72, v73
	s_waitcnt lgkmcnt(2)
	v_mfma_f32_32x32x16_bf16 v[18:33], v[118:121], v[166:169], v[18:33]
	ds_read_b64_tr_b16 v[114:115], v252 offset:28672
	ds_read_b64_tr_b16 v[116:117], v252 offset:29184
	s_waitcnt lgkmcnt(2)
	v_mfma_f32_32x32x16_bf16 v[18:33], v[214:217], v[170:173], v[18:33]
	ds_read_b64_tr_b16 v[118:119], v252 offset:29696
	ds_read_b64_tr_b16 v[120:121], v252 offset:30208
	v_exp_f32_e32 v74, v74
	v_exp_f32_e32 v75, v75
	v_exp_f32_e32 v76, v76
	v_exp_f32_e32 v77, v77
	s_waitcnt lgkmcnt(2)
	v_mfma_f32_32x32x16_bf16 v[18:33], v[114:117], v[174:177], v[18:33]
	ds_read_b64_tr_b16 v[214:215], v252 offset:30720
	ds_read_b64_tr_b16 v[216:217], v252 offset:31232
	v_add_f32_e32 v212, v74, v75
	v_add_f32_e32 v210, v212, v210
	v_add_f32_e32 v213, v77, v76
	v_add_f32_e32 v211, v213, v211
	v_cvt_pk_bf16_f32 v206, v74, v75
	v_cvt_pk_bf16_f32 v207, v76, v77
	s_waitcnt lgkmcnt(2)
	v_mfma_f32_32x32x16_bf16 v[18:33], v[118:121], v[178:181], v[18:33]
	ds_read_b64_tr_b16 v[114:115], v252 offset:31744
	ds_read_b64_tr_b16 v[116:117], v252 offset:32256
	s_waitcnt lgkmcnt(2)
	v_mfma_f32_32x32x16_bf16 v[18:33], v[214:217], v[182:185], v[18:33]
	v_exp_f32_e32 v78, v78
	v_exp_f32_e32 v79, v79
	v_exp_f32_e32 v80, v80
	v_exp_f32_e32 v81, v81
	s_waitcnt lgkmcnt(0)
	v_mfma_f32_32x32x16_bf16 v[18:33], v[114:117], v[186:189], v[18:33]
	v_add_f32_e32 v212, v78, v79
	v_add_f32_e32 v210, v212, v210
	v_add_f32_e32 v213, v81, v80
	v_add_f32_e32 v211, v213, v211
	v_cvt_pk_bf16_f32 v208, v78, v79
	v_cvt_pk_bf16_f32 v209, v80, v81
	v_add_f32_e32 v241, v211, v210
	s_waitcnt vmcnt(0) lgkmcnt(0)
	s_barrier
	ds_read_b128 v[66:69], v248
	ds_read_b128 v[70:73], v249
	ds_read_b128 v[74:77], v250
	ds_read_b128 v[78:81], v251
	v_lshl_add_u64 v[216:217], v[238:239], 0, s[44:45]
	s_mov_b32 m0, s33
	s_mov_b64 s[40:41], 0x12480000
	global_load_lds_dwordx4 v[216:217], off
	s_waitcnt lgkmcnt(3)
	v_mfma_f32_32x32x16_bf16 v[114:129], v[66:69], v[154:157], 0
	ds_read_b128 v[66:69], v248 offset:8192
	v_lshl_add_u64 v[216:217], v[232:233], 0, s[44:45]
	s_add_i32 m0, s35, 0x8400
	global_load_lds_dwordx4 v[216:217], off
	s_waitcnt lgkmcnt(3)
	v_mfma_f32_32x32x16_bf16 v[114:129], v[70:73], v[150:153], v[114:129]
	ds_read_b128 v[70:73], v249 offset:8192
	v_lshl_add_u64 v[216:217], v[234:235], 0, s[44:45]
	s_add_i32 m0, s35, 0x8800
	s_nop 0
	global_load_lds_dwordx4 v[216:217], off
	s_waitcnt lgkmcnt(3)
	v_mfma_f32_32x32x16_bf16 v[114:129], v[74:77], v[146:149], v[114:129]
	ds_read_b128 v[74:77], v250 offset:8192
	v_lshl_add_u64 v[216:217], v[236:237], 0, s[44:45]
	s_add_i32 m0, s35, 0x8c00
	s_nop 0
	global_load_lds_dwordx4 v[216:217], off
	s_waitcnt lgkmcnt(3)
	v_mfma_f32_32x32x16_bf16 v[114:129], v[78:81], v[142:145], v[114:129]
	ds_read_b128 v[78:81], v251 offset:8192
	v_lshl_add_u64 v[216:217], v[230:231], 0, s[40:41]
	s_mov_b32 m0, s7
	s_mov_b64 s[40:41], 0x12488000
	global_load_lds_dwordx4 v[216:217], off
	s_waitcnt lgkmcnt(3)
	v_mfma_f32_32x32x16_bf16 v[98:113], v[66:69], v[154:157], 0
	ds_read_b128 v[66:69], v248 offset:16384
	v_lshl_add_u64 v[216:217], v[230:231], 0, s[40:41]
	s_mov_b32 m0, s30
	s_mov_b64 s[40:41], 0x12490000
	global_load_lds_dwordx4 v[216:217], off
	s_waitcnt lgkmcnt(3)
	v_mfma_f32_32x32x16_bf16 v[98:113], v[70:73], v[150:153], v[98:113]
	ds_read_b128 v[70:73], v249 offset:16384
	v_lshl_add_u64 v[216:217], v[230:231], 0, s[40:41]
	s_mov_b32 m0, s31
	s_mov_b64 s[40:41], 0x12498000
	global_load_lds_dwordx4 v[216:217], off
	s_waitcnt lgkmcnt(3)
	v_mfma_f32_32x32x16_bf16 v[98:113], v[74:77], v[146:149], v[98:113]
	ds_read_b128 v[74:77], v250 offset:16384
	v_lshl_add_u64 v[216:217], v[230:231], 0, s[40:41]
	s_mov_b32 m0, s34
	s_nop 0
	global_load_lds_dwordx4 v[216:217], off
	s_waitcnt lgkmcnt(3)
	v_mfma_f32_32x32x16_bf16 v[98:113], v[78:81], v[142:145], v[98:113]
	v_exp_f32_e32 v114, v114
	v_exp_f32_e32 v115, v115
	v_exp_f32_e32 v116, v116
	v_exp_f32_e32 v117, v117
	ds_read_b128 v[78:81], v251 offset:16384
	s_waitcnt lgkmcnt(3)
	v_mfma_f32_32x32x16_bf16 v[82:97], v[66:69], v[154:157], 0
	v_add_f32_e32 v210, v114, v115
	v_add_f32_e32 v211, v117, v116
	v_cvt_pk_bf16_f32 v158, v114, v115
	v_cvt_pk_bf16_f32 v159, v116, v117
	ds_read_b128 v[174:177], v248 offset:24576
	s_waitcnt lgkmcnt(3)
	v_mfma_f32_32x32x16_bf16 v[82:97], v[70:73], v[150:153], v[82:97]
	v_exp_f32_e32 v118, v118
	v_exp_f32_e32 v119, v119
	v_exp_f32_e32 v120, v120
	v_exp_f32_e32 v121, v121
	ds_read_b128 v[178:181], v249 offset:24576
	s_waitcnt lgkmcnt(3)
	v_mfma_f32_32x32x16_bf16 v[82:97], v[74:77], v[146:149], v[82:97]
	v_add_f32_e32 v212, v118, v119
	v_add_f32_e32 v210, v212, v210
	v_add_f32_e32 v213, v121, v120
	v_add_f32_e32 v211, v213, v211
	v_cvt_pk_bf16_f32 v160, v118, v119
	v_cvt_pk_bf16_f32 v161, v120, v121
	ds_read_b128 v[182:185], v250 offset:24576
	s_waitcnt lgkmcnt(3)
	v_mfma_f32_32x32x16_bf16 v[82:97], v[78:81], v[142:145], v[82:97]
	v_exp_f32_e32 v122, v122
	v_exp_f32_e32 v123, v123
	v_exp_f32_e32 v124, v124
	v_exp_f32_e32 v125, v125
	ds_read_b128 v[186:189], v251 offset:24576
	s_waitcnt lgkmcnt(3)
	v_mfma_f32_32x32x16_bf16 v[66:81], v[174:177], v[154:157], 0
	v_add_f32_e32 v212, v122, v123
	v_add_f32_e32 v210, v212, v210
	v_add_f32_e32 v213, v125, v124
	v_add_f32_e32 v211, v213, v211
	v_cvt_pk_bf16_f32 v162, v122, v123
	v_cvt_pk_bf16_f32 v163, v124, v125
	s_waitcnt lgkmcnt(2)
	v_mfma_f32_32x32x16_bf16 v[66:81], v[178:181], v[150:153], v[66:81]
	v_exp_f32_e32 v126, v126
	v_exp_f32_e32 v127, v127
	v_exp_f32_e32 v128, v128
	v_exp_f32_e32 v129, v129
	ds_read_b64_tr_b16 v[214:215], v253
	ds_read_b64_tr_b16 v[216:217], v253 offset:512
	s_waitcnt lgkmcnt(3)
	v_mfma_f32_32x32x16_bf16 v[66:81], v[182:185], v[146:149], v[66:81]
	v_add_f32_e32 v212, v126, v127
	v_add_f32_e32 v210, v212, v210
	v_add_f32_e32 v213, v129, v128
	v_add_f32_e32 v211, v213, v211
	v_cvt_pk_bf16_f32 v164, v126, v127
	v_cvt_pk_bf16_f32 v165, v128, v129
	ds_read_b64_tr_b16 v[114:115], v253 offset:1024
	ds_read_b64_tr_b16 v[116:117], v253 offset:1536
	s_waitcnt lgkmcnt(4)
	v_mfma_f32_32x32x16_bf16 v[66:81], v[186:189], v[142:145], v[66:81]
	v_exp_f32_e32 v98, v98
	v_exp_f32_e32 v99, v99
	v_exp_f32_e32 v100, v100
	v_exp_f32_e32 v101, v101
	s_waitcnt lgkmcnt(2)
	v_mfma_f32_32x32x16_bf16 v[2:17], v[214:217], v[130:133], v[2:17]
	ds_read_b64_tr_b16 v[118:119], v253 offset:2048
	ds_read_b64_tr_b16 v[120:121], v253 offset:2560
	v_add_f32_e32 v212, v98, v99
	v_add_f32_e32 v210, v212, v210
	v_add_f32_e32 v213, v101, v100
	v_add_f32_e32 v211, v213, v211
	v_cvt_pk_bf16_f32 v166, v98, v99
	v_cvt_pk_bf16_f32 v167, v100, v101
	s_waitcnt lgkmcnt(2)
	v_mfma_f32_32x32x16_bf16 v[2:17], v[114:117], v[134:137], v[2:17]
	ds_read_b64_tr_b16 v[214:215], v253 offset:3072
	ds_read_b64_tr_b16 v[216:217], v253 offset:3584
	s_waitcnt lgkmcnt(2)
	v_mfma_f32_32x32x16_bf16 v[2:17], v[118:121], v[138:141], v[2:17]
	ds_read_b64_tr_b16 v[114:115], v253 offset:4096
	ds_read_b64_tr_b16 v[116:117], v253 offset:4608
	v_exp_f32_e32 v102, v102
	v_exp_f32_e32 v103, v103
	v_exp_f32_e32 v104, v104
	v_exp_f32_e32 v105, v105
	s_waitcnt lgkmcnt(2)
	v_mfma_f32_32x32x16_bf16 v[2:17], v[214:217], v[190:193], v[2:17]
	ds_read_b64_tr_b16 v[118:119], v253 offset:5120
	ds_read_b64_tr_b16 v[120:121], v253 offset:5632
	v_add_f32_e32 v212, v102, v103
	v_add_f32_e32 v210, v212, v210
	v_add_f32_e32 v213, v105, v104
	v_add_f32_e32 v211, v213, v211
	v_cvt_pk_bf16_f32 v168, v102, v103
	v_cvt_pk_bf16_f32 v169, v104, v105
	s_waitcnt lgkmcnt(2)
	v_mfma_f32_32x32x16_bf16 v[2:17], v[114:117], v[194:197], v[2:17]
	ds_read_b64_tr_b16 v[214:215], v253 offset:6144
	ds_read_b64_tr_b16 v[216:217], v253 offset:6656
	s_waitcnt lgkmcnt(2)
	v_mfma_f32_32x32x16_bf16 v[2:17], v[118:121], v[198:201], v[2:17]
	ds_read_b64_tr_b16 v[114:115], v253 offset:7168
	ds_read_b64_tr_b16 v[116:117], v253 offset:7680
	v_exp_f32_e32 v106, v106
	v_exp_f32_e32 v107, v107
	v_exp_f32_e32 v108, v108
	v_exp_f32_e32 v109, v109
	s_waitcnt lgkmcnt(2)
	v_mfma_f32_32x32x16_bf16 v[2:17], v[214:217], v[202:205], v[2:17]
	ds_read_b64_tr_b16 v[118:119], v253 offset:8192
	ds_read_b64_tr_b16 v[120:121], v253 offset:8704
	v_add_f32_e32 v212, v106, v107
	v_add_f32_e32 v210, v212, v210
	v_add_f32_e32 v213, v109, v108
	v_add_f32_e32 v211, v213, v211
	v_cvt_pk_bf16_f32 v170, v106, v107
	v_cvt_pk_bf16_f32 v171, v108, v109
	s_waitcnt lgkmcnt(2)
	v_mfma_f32_32x32x16_bf16 v[2:17], v[114:117], v[206:209], v[2:17]
	ds_read_b64_tr_b16 v[214:215], v253 offset:9216
	ds_read_b64_tr_b16 v[216:217], v253 offset:9728
	v_exp_f32_e32 v110, v110
	v_exp_f32_e32 v111, v111
	v_exp_f32_e32 v112, v112
	v_exp_f32_e32 v113, v113
	s_waitcnt lgkmcnt(2)
	v_mfma_f32_32x32x16_bf16 v[50:65], v[118:121], v[130:133], v[50:65]
	ds_read_b64_tr_b16 v[114:115], v253 offset:10240
	ds_read_b64_tr_b16 v[116:117], v253 offset:10752
	s_waitcnt lgkmcnt(2)
	v_mfma_f32_32x32x16_bf16 v[50:65], v[214:217], v[134:137], v[50:65]
	ds_read_b64_tr_b16 v[118:119], v253 offset:11264
	ds_read_b64_tr_b16 v[120:121], v253 offset:11776
	v_add_f32_e32 v212, v110, v111
	v_add_f32_e32 v210, v212, v210
	v_add_f32_e32 v213, v113, v112
	v_add_f32_e32 v211, v213, v211
	v_cvt_pk_bf16_f32 v172, v110, v111
	v_cvt_pk_bf16_f32 v173, v112, v113
	s_waitcnt lgkmcnt(2)
	v_mfma_f32_32x32x16_bf16 v[50:65], v[114:117], v[138:141], v[50:65]
	ds_read_b64_tr_b16 v[214:215], v253 offset:12288
	ds_read_b64_tr_b16 v[216:217], v253 offset:12800
	v_exp_f32_e32 v82, v82
	v_exp_f32_e32 v83, v83
	v_exp_f32_e32 v84, v84
	v_exp_f32_e32 v85, v85
	s_waitcnt lgkmcnt(2)
	v_mfma_f32_32x32x16_bf16 v[50:65], v[118:121], v[190:193], v[50:65]
	ds_read_b64_tr_b16 v[114:115], v253 offset:13312
	ds_read_b64_tr_b16 v[116:117], v253 offset:13824
	s_waitcnt lgkmcnt(2)
	v_mfma_f32_32x32x16_bf16 v[50:65], v[214:217], v[194:197], v[50:65]
	ds_read_b64_tr_b16 v[118:119], v253 offset:14336
	ds_read_b64_tr_b16 v[120:121], v253 offset:14848
	v_add_f32_e32 v212, v82, v83
	v_add_f32_e32 v210, v212, v210
	v_add_f32_e32 v213, v85, v84
	v_add_f32_e32 v211, v213, v211
	v_cvt_pk_bf16_f32 v174, v82, v83
	v_cvt_pk_bf16_f32 v175, v84, v85
	s_waitcnt lgkmcnt(2)
; #define D8_FULL(WC_, WN_, t_, MASK_) do { const int tt = (t_); D8_HEAD(tt) D8_QKP(tt + 1, MASK_) D8_PVX(tt, WC_, true, WN_) } while (0)
; __device__ __forceinline__ void df_unit_p128(ATT_LAS unsigned char* lds, const bf16_t* Q, const bf16_t* __restrict__ K, const bf16_t* __restrict__ V, bf16_t* O, int b, int h, int qb,
;                                              float lam, float post, const float* __restrict__ sub_g, const int wv) {
;     ...
;     for (; T + 2 <= qb - 1; T += 2) { D8_FULL(wa, wb, T, false); D8_FULL(wb, wa, T + 1, false); }
	v_mfma_f32_32x32x16_bf16 v[50:65], v[114:117], v[198:201], v[50:65]
	ds_read_b64_tr_b16 v[214:215], v253 offset:15360
	ds_read_b64_tr_b16 v[216:217], v253 offset:15872
	v_exp_f32_e32 v86, v86
	v_exp_f32_e32 v87, v87
	v_exp_f32_e32 v88, v88
	v_exp_f32_e32 v89, v89
	s_waitcnt lgkmcnt(2)
	v_mfma_f32_32x32x16_bf16 v[50:65], v[118:121], v[202:205], v[50:65]
	ds_read_b64_tr_b16 v[114:115], v253 offset:16384
	ds_read_b64_tr_b16 v[116:117], v253 offset:16896
	v_add_f32_e32 v212, v86, v87
	v_add_f32_e32 v210, v212, v210
	v_add_f32_e32 v213, v89, v88
	v_add_f32_e32 v211, v213, v211
	v_cvt_pk_bf16_f32 v176, v86, v87
	v_cvt_pk_bf16_f32 v177, v88, v89
	s_waitcnt lgkmcnt(2)
	v_mfma_f32_32x32x16_bf16 v[50:65], v[214:217], v[206:209], v[50:65]
	ds_read_b64_tr_b16 v[118:119], v253 offset:17408
	ds_read_b64_tr_b16 v[120:121], v253 offset:17920
	s_waitcnt lgkmcnt(2)
	v_mfma_f32_32x32x16_bf16 v[34:49], v[114:117], v[130:133], v[34:49]
	ds_read_b64_tr_b16 v[214:215], v253 offset:18432
	ds_read_b64_tr_b16 v[216:217], v253 offset:18944
	v_exp_f32_e32 v90, v90
	v_exp_f32_e32 v91, v91
	v_exp_f32_e32 v92, v92
	v_exp_f32_e32 v93, v93
	s_waitcnt lgkmcnt(2)
	v_mfma_f32_32x32x16_bf16 v[34:49], v[118:121], v[134:137], v[34:49]
	ds_read_b64_tr_b16 v[114:115], v253 offset:19456
	ds_read_b64_tr_b16 v[116:117], v253 offset:19968
	v_add_f32_e32 v212, v90, v91
	v_add_f32_e32 v210, v212, v210
	v_add_f32_e32 v213, v93, v92
	v_add_f32_e32 v211, v213, v211
	v_cvt_pk_bf16_f32 v178, v90, v91
	v_cvt_pk_bf16_f32 v179, v92, v93
	s_waitcnt lgkmcnt(2)
	v_mfma_f32_32x32x16_bf16 v[34:49], v[214:217], v[138:141], v[34:49]
	ds_read_b64_tr_b16 v[118:119], v253 offset:20480
	ds_read_b64_tr_b16 v[120:121], v253 offset:20992
	v_exp_f32_e32 v94, v94
	v_exp_f32_e32 v95, v95
	v_exp_f32_e32 v96, v96
	v_exp_f32_e32 v97, v97
	s_waitcnt lgkmcnt(2)
	v_mfma_f32_32x32x16_bf16 v[34:49], v[114:117], v[190:193], v[34:49]
	ds_read_b64_tr_b16 v[214:215], v253 offset:21504
	ds_read_b64_tr_b16 v[216:217], v253 offset:22016
	s_waitcnt lgkmcnt(2)
	v_mfma_f32_32x32x16_bf16 v[34:49], v[118:121], v[194:197], v[34:49]
	ds_read_b64_tr_b16 v[114:115], v253 offset:22528
	ds_read_b64_tr_b16 v[116:117], v253 offset:23040
	v_add_f32_e32 v212, v94, v95
	v_add_f32_e32 v210, v212, v210
	v_add_f32_e32 v213, v97, v96
	v_add_f32_e32 v211, v213, v211
	v_cvt_pk_bf16_f32 v180, v94, v95
	v_cvt_pk_bf16_f32 v181, v96, v97
	s_waitcnt lgkmcnt(2)
	v_mfma_f32_32x32x16_bf16 v[34:49], v[214:217], v[198:201], v[34:49]
	ds_read_b64_tr_b16 v[118:119], v253 offset:23552
	ds_read_b64_tr_b16 v[120:121], v253 offset:24064
	v_exp_f32_e32 v66, v66
	v_exp_f32_e32 v67, v67
	v_exp_f32_e32 v68, v68
	v_exp_f32_e32 v69, v69
	s_waitcnt lgkmcnt(2)
	v_mfma_f32_32x32x16_bf16 v[34:49], v[114:117], v[202:205], v[34:49]
	ds_read_b64_tr_b16 v[214:215], v253 offset:24576
	ds_read_b64_tr_b16 v[216:217], v253 offset:25088
	s_waitcnt lgkmcnt(2)
	v_mfma_f32_32x32x16_bf16 v[34:49], v[118:121], v[206:209], v[34:49]
	ds_read_b64_tr_b16 v[114:115], v253 offset:25600
	ds_read_b64_tr_b16 v[116:117], v253 offset:26112
	v_add_f32_e32 v212, v66, v67
	v_add_f32_e32 v210, v212, v210
	v_add_f32_e32 v213, v69, v68
	v_add_f32_e32 v211, v213, v211
	v_cvt_pk_bf16_f32 v182, v66, v67
	v_cvt_pk_bf16_f32 v183, v68, v69
	s_waitcnt lgkmcnt(2)
	v_mfma_f32_32x32x16_bf16 v[18:33], v[214:217], v[130:133], v[18:33]
	ds_read_b64_tr_b16 v[118:119], v253 offset:26624
	ds_read_b64_tr_b16 v[120:121], v253 offset:27136
	v_exp_f32_e32 v70, v70
	v_exp_f32_e32 v71, v71
	v_exp_f32_e32 v72, v72
	v_exp_f32_e32 v73, v73
	s_waitcnt lgkmcnt(2)
	v_mfma_f32_32x32x16_bf16 v[18:33], v[114:117], v[134:137], v[18:33]
	ds_read_b64_tr_b16 v[214:215], v253 offset:27648
	ds_read_b64_tr_b16 v[216:217], v253 offset:28160
	v_add_f32_e32 v212, v70, v71
	v_add_f32_e32 v210, v212, v210
	v_add_f32_e32 v213, v73, v72
	v_add_f32_e32 v211, v213, v211
	v_cvt_pk_bf16_f32 v184, v70, v71
	v_cvt_pk_bf16_f32 v185, v72, v73
	s_waitcnt lgkmcnt(2)
	v_mfma_f32_32x32x16_bf16 v[18:33], v[118:121], v[138:141], v[18:33]
	ds_read_b64_tr_b16 v[114:115], v253 offset:28672
	ds_read_b64_tr_b16 v[116:117], v253 offset:29184
	s_waitcnt lgkmcnt(2)
	v_mfma_f32_32x32x16_bf16 v[18:33], v[214:217], v[190:193], v[18:33]
	ds_read_b64_tr_b16 v[118:119], v253 offset:29696
	ds_read_b64_tr_b16 v[120:121], v253 offset:30208
	v_exp_f32_e32 v74, v74
	v_exp_f32_e32 v75, v75
	v_exp_f32_e32 v76, v76
	v_exp_f32_e32 v77, v77
	s_waitcnt lgkmcnt(2)
	v_mfma_f32_32x32x16_bf16 v[18:33], v[114:117], v[194:197], v[18:33]
	ds_read_b64_tr_b16 v[214:215], v253 offset:30720
	ds_read_b64_tr_b16 v[216:217], v253 offset:31232
	v_add_f32_e32 v212, v74, v75
	v_add_f32_e32 v210, v212, v210
	v_add_f32_e32 v213, v77, v76
	v_add_f32_e32 v211, v213, v211
	v_cvt_pk_bf16_f32 v186, v74, v75
	v_cvt_pk_bf16_f32 v187, v76, v77
	s_waitcnt lgkmcnt(2)
	v_mfma_f32_32x32x16_bf16 v[18:33], v[118:121], v[198:201], v[18:33]
	ds_read_b64_tr_b16 v[114:115], v253 offset:31744
	ds_read_b64_tr_b16 v[116:117], v253 offset:32256
	s_waitcnt lgkmcnt(2)
	v_mfma_f32_32x32x16_bf16 v[18:33], v[214:217], v[202:205], v[18:33]
	v_exp_f32_e32 v78, v78
	v_exp_f32_e32 v79, v79
	v_exp_f32_e32 v80, v80
	v_exp_f32_e32 v81, v81
	s_waitcnt lgkmcnt(0)
	v_mfma_f32_32x32x16_bf16 v[18:33], v[114:117], v[206:209], v[18:33]
	v_add_f32_e32 v212, v78, v79
	v_add_f32_e32 v210, v212, v210
	v_add_f32_e32 v213, v81, v80
	v_add_f32_e32 v211, v213, v211
	v_cvt_pk_bf16_f32 v188, v78, v79
	v_cvt_pk_bf16_f32 v189, v80, v81
	s_add_i32 s39, s39, 2
	s_add_u32 s16, s16, 0x80000
	v_add_f32_e32 v212, v247, v241
	v_add_f32_e32 v213, v211, v210
	s_addc_u32 s17, s17, 0
	s_add_i32 s18, s18, 4
	s_cmp_lt_u32 s18, s25
	v_add_f32_e32 v247, v212, v213
	s_cbranch_scc1 .LBB0_220
	s_nop 0
	s_mov_b32 s19, s55
	s_lshl_b64 s[16:17], s[18:19], 18
	v_mov_b64_e32 v[226:227], 0x600
	v_mov_b64_e32 v[228:229], 0x5ff
	v_mov_b64_e32 v[232:233], 0x200
	v_mov_b64_e32 v[234:235], 0x1ff
	s_add_i32 s18, s23, 30
	s_cmp_ge_i32 s39, s18
	s_mov_b64 s[18:19], -1
	s_cbranch_scc0 .LBB0_229
	s_branch .LBB0_223
